# softmax segment rewrite (uniform-bias fast path, permlane max, hoisted reads, prio 3) + bias table staged once; MFMA segment as baseline
# baseline (speedup 1.0000x reference)
; __device__ __forceinline__ void d2_qk(const LAS unsigned char* Kb, const v8s (&Q)[4], v16f& S) {
;     const v16f z = {0.f, 0.f, 0.f, 0.f, 0.f, 0.f, 0.f, 0.f, 0.f, 0.f, 0.f, 0.f, 0.f, 0.f, 0.f, 0.f};
;     const v8s k0 = *(const LAS v8s*)Kb, k1 = *(const LAS v8s*)(Kb + 32), k2 = *(const LAS v8s*)(Kb + 64), k3 = *(const LAS v8s*)(Kb + 96);
;     __builtin_amdgcn_sched_barrier(0);
;     S = MFMA32(k0, Q[0], z); S = MFMA32(k1, Q[1], S); S = MFMA32(k2, Q[2], S); S = MFMA32(k3, Q[3], S);
;     __builtin_amdgcn_sched_barrier(0);
; }
; __device__ __forceinline__ void d2_softmax(v16f& S, const float c1, const LAS float* tp, float& m, float& l, v16f (&O)[4], v8s (&P)[2]) {
;     float tmax = NEGBIG;
; #pragma unroll
;     for (int i = 0; i < 16; ++i) { S[i] = S[i] * c1 + tp[(i & 3) + 8 * (i >> 2)]; tmax = fmaxf(tmax, S[i]); }
;     tmax = fmaxf(tmax, __shfl_xor(tmax, 32));
;     const float mo = m;
;     if (__any(tmax > mo + 8.f)) {
;         const float mn = (tmax > mo + 8.f) ? tmax : mo;
;         const float alpha = __builtin_amdgcn_exp2f(mo - mn);
;         l *= alpha;
; #pragma unroll
;         for (int eb = 0; eb < 4; ++eb)
; #pragma unroll
;             for (int i = 0; i < 16; ++i) O[eb][i] *= alpha;
;         m = mn;
;     }
;     const float mc = m;
;     float ps = 0.f;
; #pragma unroll
;     for (int i = 0; i < 16; ++i) { S[i] = __builtin_amdgcn_exp2f(S[i] - mc); ps += S[i]; }
;     l += ps;
; #pragma unroll
;     for (int s2 = 0; s2 < 2; ++s2) { v4u w; w.x = pk2(S[8 * s2 + 0], S[8 * s2 + 1]); w.y = pk2(S[8 * s2 + 2], S[8 * s2 + 3]); w.z = pk2(S[8 * s2 + 4], S[8 * s2 + 5]); w.w = pk2(S[8 * s2 + 6], S[8 * s2 + 7]);
;         P[s2] = __builtin_bit_cast(v8s, w); }
; }
; __device__ __forceinline__ void d2_pv(const LAS unsigned char* vb0, const v8s (&P)[2], v16f (&O)[4]) {
;     const LAS unsigned char* va = vb0; const LAS unsigned char* vc = vb0 + 16 * 320;
;     const v4s l0 = TRR(va), h0 = TRR(va + 2560), l1 = TRR(va + 64), h1 = TRR(va + 2624), l2 = TRR(va + 128), h2 = TRR(va + 2688), l3 = TRR(va + 192), h3 = TRR(va + 2752);
;     __builtin_amdgcn_sched_barrier(0);
;     const v4s m0 = TRR(vc), n0 = TRR(vc + 2560), m1 = TRR(vc + 64), n1 = TRR(vc + 2624), m2 = TRR(vc + 128), n2 = TRR(vc + 2688), m3 = TRR(vc + 192), n3 = TRR(vc + 2752);
;     O[0] = MFMA32(__builtin_shufflevector(l0, h0, 0, 1, 2, 3, 4, 5, 6, 7), P[0], O[0]);
.LBB0_333:
	s_mul_i32 s19, s18, 0x4800
	v_add_u32_e32 v0, s19, v181
	ds_read_b128 v[66:69], v0
	ds_read_b128 v[82:85], v0 offset:32
	ds_read_b128 v[86:89], v0 offset:64
	ds_read_b128 v[90:93], v0 offset:96
	s_waitcnt lgkmcnt(3)
	v_mfma_f32_32x32x16_bf16 v[66:81], v[66:69], v[98:101], 0
	s_waitcnt lgkmcnt(2)
	v_mfma_f32_32x32x16_bf16 v[66:81], v[82:85], v[102:105], v[66:81]
	s_waitcnt lgkmcnt(1)
	v_mfma_f32_32x32x16_bf16 v[66:81], v[86:89], v[106:109], v[66:81]
	s_waitcnt lgkmcnt(0)
	v_mfma_f32_32x32x16_bf16 v[66:81], v[90:93], v[110:113], v[66:81]
	ds_read_b128 v[82:85], v0 offset:4608
	ds_read_b128 v[156:159], v0 offset:4640
	ds_read_b128 v[186:189], v0 offset:4672
	ds_read_b128 v[190:193], v0 offset:4704
	s_waitcnt lgkmcnt(3)
	v_mfma_f32_32x32x16_bf16 v[82:97], v[82:85], v[98:101], 0
	s_waitcnt lgkmcnt(2)
	v_mfma_f32_32x32x16_bf16 v[82:97], v[156:159], v[102:105], v[82:97]
	s_waitcnt lgkmcnt(1)
	v_mfma_f32_32x32x16_bf16 v[82:97], v[186:189], v[106:109], v[82:97]
	s_waitcnt lgkmcnt(0)
	v_mfma_f32_32x32x16_bf16 v[82:97], v[190:193], v[110:113], v[82:97]
	s_cmp_eq_u32 s6, 0
	s_cbranch_scc1 .LBB0_335
	s_xor_b32 s18, s18, 1
	s_mulk_i32 s18, 0x5000
	v_add_u32_e32 v0, s18, v180
	ds_read_b64_tr_b16 v[156:157], v0 offset:36864
	ds_read_b64_tr_b16 v[186:187], v0 offset:36928
	ds_read_b64_tr_b16 v[190:191], v0 offset:36992
	ds_read_b64_tr_b16 v[194:195], v0 offset:37056
	ds_read_b64_tr_b16 v[158:159], v0 offset:39424
	ds_read_b64_tr_b16 v[188:189], v0 offset:39488
	ds_read_b64_tr_b16 v[192:193], v0 offset:39552
	ds_read_b64_tr_b16 v[196:197], v0 offset:39616
	s_waitcnt lgkmcnt(3)
	v_mfma_f32_32x32x16_bf16 v[50:65], v[156:159], v[134:137], v[50:65]
	s_waitcnt lgkmcnt(2)
	v_mfma_f32_32x32x16_bf16 v[34:49], v[186:189], v[134:137], v[34:49]
	s_waitcnt lgkmcnt(1)
	v_mfma_f32_32x32x16_bf16 v[18:33], v[190:193], v[134:137], v[18:33]
	ds_read_b64_tr_b16 v[156:157], v0 offset:41984
	ds_read_b64_tr_b16 v[186:187], v0 offset:42048
	ds_read_b64_tr_b16 v[190:191], v0 offset:42112
	ds_read_b64_tr_b16 v[198:199], v0 offset:42176
	ds_read_b64_tr_b16 v[158:159], v0 offset:44544
	ds_read_b64_tr_b16 v[188:189], v0 offset:44608
	ds_read_b64_tr_b16 v[192:193], v0 offset:44672
	ds_read_b64_tr_b16 v[200:201], v0 offset:44736
	s_waitcnt lgkmcnt(8)
	v_mfma_f32_32x32x16_bf16 v[2:17], v[194:197], v[134:137], v[2:17]
	s_waitcnt lgkmcnt(3)
	v_mfma_f32_32x32x16_bf16 v[50:65], v[156:159], v[130:133], v[50:65]
	s_waitcnt lgkmcnt(2)
	v_mfma_f32_32x32x16_bf16 v[34:49], v[186:189], v[130:133], v[34:49]
	s_waitcnt lgkmcnt(1)
	v_mfma_f32_32x32x16_bf16 v[18:33], v[190:193], v[130:133], v[18:33]
	s_waitcnt lgkmcnt(0)
	v_mfma_f32_32x32x16_bf16 v[2:17], v[198:201], v[130:133], v[2:17]
	ds_read_b64_tr_b16 v[156:157], v0 offset:47104
	ds_read_b64_tr_b16 v[186:187], v0 offset:47168
	ds_read_b64_tr_b16 v[190:191], v0 offset:47232
	ds_read_b64_tr_b16 v[194:195], v0 offset:47296
	ds_read_b64_tr_b16 v[158:159], v0 offset:49664
	ds_read_b64_tr_b16 v[188:189], v0 offset:49728
	ds_read_b64_tr_b16 v[192:193], v0 offset:49792
	ds_read_b64_tr_b16 v[196:197], v0 offset:49856
	s_waitcnt lgkmcnt(3)
	v_mfma_f32_32x32x16_bf16 v[50:65], v[156:159], v[142:145], v[50:65]
	s_waitcnt lgkmcnt(2)
	v_mfma_f32_32x32x16_bf16 v[34:49], v[186:189], v[142:145], v[34:49]
	s_waitcnt lgkmcnt(1)
	v_mfma_f32_32x32x16_bf16 v[18:33], v[190:193], v[142:145], v[18:33]
	ds_read_b64_tr_b16 v[156:157], v0 offset:52224
	ds_read_b64_tr_b16 v[186:187], v0 offset:52288
	ds_read_b64_tr_b16 v[190:191], v0 offset:52352
	ds_read_b64_tr_b16 v[198:199], v0 offset:52416
	ds_read_b64_tr_b16 v[158:159], v0 offset:54784
	ds_read_b64_tr_b16 v[188:189], v0 offset:54848
	ds_read_b64_tr_b16 v[192:193], v0 offset:54912
	ds_read_b64_tr_b16 v[200:201], v0 offset:54976
	s_waitcnt lgkmcnt(8)
	v_mfma_f32_32x32x16_bf16 v[2:17], v[194:197], v[142:145], v[2:17]
	s_waitcnt lgkmcnt(3)
	v_mfma_f32_32x32x16_bf16 v[50:65], v[156:159], v[138:141], v[50:65]
	s_waitcnt lgkmcnt(2)
	v_mfma_f32_32x32x16_bf16 v[34:49], v[186:189], v[138:141], v[34:49]
	s_waitcnt lgkmcnt(1)
	v_mfma_f32_32x32x16_bf16 v[18:33], v[190:193], v[138:141], v[18:33]
	s_waitcnt lgkmcnt(0)
	v_mfma_f32_32x32x16_bf16 v[2:17], v[198:201], v[138:141], v[2:17]
.LBB0_335:
	s_andn2_saveexec_b64 s[18:19], s[10:11]
	s_cbranch_execz .LBB0_341
	s_setprio 3
	v_readfirstlane_b32 s98, v183
	v_med3_i32 v0, v183, s16, v214
	v_add_u32_e32 v156, 32, v183
	s_mov_b32 s100, 0xfff9f990
	s_mov_b32 s101, -1
	v_lshl_add_u32 v0, v0, 2, s23
	v_med3_i32 v156, v156, s16, v214
	s_add_i32 s99, s98, 32
	s_abs_i32 s98, s98
	s_abs_i32 s99, s99
	s_lshr_b32 s98, s98, 5
	s_lshr_b32 s99, s99, 5
	v_add_u32_e32 v0, 0xa80, v0
	v_lshl_add_u32 v156, v156, 2, s23
	v_add_u32_e32 v156, 0xa80, v156
	s_bitcmp1_b64 s[100:101], s99
	s_cbranch_scc1 .Ld2x0_i1f
	ds_read2_b32 v[186:187], v156 offset1:1
	ds_read2_b32 v[188:189], v156 offset0:2 offset1:3
	ds_read2_b32 v[190:191], v156 offset0:8 offset1:9
	ds_read2_b32 v[192:193], v156 offset0:10 offset1:11
	ds_read2_b32 v[194:195], v156 offset0:16 offset1:17
	ds_read2_b32 v[196:197], v156 offset0:18 offset1:19
	ds_read2_b32 v[198:199], v156 offset0:24 offset1:25
	ds_read2_b32 v[200:201], v156 offset0:26 offset1:27
	s_branch .Ld2x0_i1d
